# prep weight conversion: norm-gain loads no longer serialize the weight loads (gains preset to 1.0 in their own registers, multiplies after the single wait)
# speedup vs baseline: 1.0001x; 1.0001x over previous
; DI void prep_wt(const float* __restrict__ src, u16* __restrict__ dst, int K, int N, int Npad,
;                 const float* __restrict__ gain, float* tile) {
;     ...
;   for (int t0 = blockIdx.x; t0 < nt4; t0 += 4 * gridDim.x) {
;     f32x4 v[4][2];
; #pragma unroll
;     for (int j = 0; j < 4; ++j) {
;       const int t = t0 + j * gridDim.x;
;       const int kt = t % tk, nt = t / tk;
; #pragma unroll
;       for (int i = 0; i < 2; ++i) {
;         const int e = tid + NTHR * i; const int kk = e >> 4, n4 = (e & 15) * 4; const int n = nt * 64 + n4;
;         v[j][i] = (f32x4){0.f, 0.f, 0.f, 0.f};
;         if (t < nt4 && n < N) {
;           v[j][i] = *(const f32x4*)(src + (size_t)(kt * 64 + kk) * N + n);
;           if (gain) v[j][i] *= gain[kt * 64 + kk];
;         }
;       }
;     }
.LBB0_23:
	s_ashr_i32 s0, s65, 31
	s_lshr_b32 s0, s0, 28
	s_add_i32 s0, s65, s0
	s_ashr_i32 s2, s0, 4
	s_lshl_b32 s83, s2, 6
	v_or_b32_e32 v0, s83, v39
	s_lshl_b32 s2, s2, 10
	v_ashrrev_i32_e32 v1, 31, v0
	v_cmp_gt_i32_e64 s[0:1], s78, v0
	s_sub_i32 s84, 0, s2
	v_lshl_add_u64 v[8:9], v[0:1], 2, s[42:43]
	v_mov_b32_e32 v0, 0
	v_cmp_ne_u32_e64 s[2:3], 1, v38
	v_mov_b32_e32 v4, 0
	v_mov_b32_e32 v5, 0
	v_mov_b32_e32 v6, 0
	v_mov_b32_e32 v7, 0
	v_mov_b32_e32 v60, 1.0
	v_mov_b32_e32 v62, 1.0
	v_mov_b32_e32 v64, 1.0
	v_mov_b32_e32 v66, 1.0
	v_mov_b32_e32 v68, 1.0
	v_mov_b32_e32 v70, 1.0
	v_mov_b32_e32 v72, 1.0
	v_mov_b32_e32 v74, 1.0
	s_and_saveexec_b64 s[46:47], s[0:1]
	s_cbranch_execz .LBB0_26
	s_add_i32 s48, s84, s64
	v_add_u32_e32 v2, s48, v42
	v_mad_i64_i32 v[4:5], s[48:49], v2, s79, v[8:9]
	global_load_dwordx4 v[4:7], v[4:5], off
	s_and_b64 vcc, exec, s[2:3]
	s_cbranch_vccnz .LBB0_26
	v_ashrrev_i32_e32 v3, 31, v2
	v_lshl_add_u64 v[2:3], v[2:3], 2, s[40:41]
	global_load_dword v60, v[2:3], off
.LBB0_26:
	s_or_b64 exec, exec, s[46:47]
	v_mov_b32_e32 v1, 0
	v_mov_b32_e32 v2, 0
	v_mov_b32_e32 v3, 0
	s_and_saveexec_b64 s[46:47], s[0:1]
	s_cbranch_execz .LBB0_29
	s_add_i32 s0, s84, s64
	v_add_u32_e32 v10, s0, v43
	v_mad_i64_i32 v[0:1], s[0:1], v10, s79, v[8:9]
	global_load_dwordx4 v[0:3], v[0:1], off
	s_and_b64 vcc, exec, s[2:3]
	s_cbranch_vccnz .LBB0_29
	v_ashrrev_i32_e32 v11, 31, v10
	v_lshl_add_u64 v[8:9], v[10:11], 2, s[40:41]
	global_load_dword v62, v[8:9], off
.LBB0_29:
	s_or_b64 exec, exec, s[46:47]
	s_add_i32 s0, s60, s65
	s_ashr_i32 s1, s0, 31
	s_lshr_b32 s1, s1, 28
	s_add_i32 s1, s0, s1
	s_and_b32 s46, s1, 0x3fffff0
	s_lshl_b32 s1, s1, 2
	s_sub_i32 s50, s0, s46
	s_andn2_b32 s1, s1, 63
	v_or_b32_e32 v8, s1, v39
	s_cmpk_lt_i32 s0, 0x240
	s_cselect_b64 s[46:47], -1, 0
	v_cmp_gt_i32_e32 vcc, s78, v8
	v_ashrrev_i32_e32 v9, 31, v8
	s_and_b64 s[48:49], s[46:47], vcc
	s_lshl_b32 s0, s50, 6
	v_lshl_add_u64 v[16:17], v[8:9], 2, s[42:43]
	v_mov_b32_e32 v8, 0
	v_mov_b32_e32 v12, 0
	v_mov_b32_e32 v13, 0
	v_mov_b32_e32 v14, 0
	v_mov_b32_e32 v15, 0
	s_and_saveexec_b64 s[50:51], s[48:49]
	s_cbranch_execz .LBB0_32
	v_add_u32_e32 v10, s0, v42
	v_mad_i64_i32 v[12:13], s[52:53], v10, s79, v[16:17]
	global_load_dwordx4 v[12:15], v[12:13], off
	s_and_b64 vcc, exec, s[2:3]
	s_cbranch_vccnz .LBB0_32
	v_ashrrev_i32_e32 v11, 31, v10
	v_lshl_add_u64 v[10:11], v[10:11], 2, s[40:41]
	global_load_dword v64, v[10:11], off
.LBB0_32:
	s_or_b64 exec, exec, s[50:51]
	v_mov_b32_e32 v9, 0
	v_mov_b32_e32 v10, 0
	v_mov_b32_e32 v11, 0
	s_and_saveexec_b64 s[50:51], s[48:49]
	s_cbranch_execz .LBB0_35
	v_add_u32_e32 v18, s0, v43
	v_mad_i64_i32 v[8:9], s[48:49], v18, s79, v[16:17]
	global_load_dwordx4 v[8:11], v[8:9], off
	s_and_b64 vcc, exec, s[2:3]
	s_cbranch_vccnz .LBB0_35
	v_ashrrev_i32_e32 v19, 31, v18
	v_lshl_add_u64 v[16:17], v[18:19], 2, s[40:41]
	global_load_dword v66, v[16:17], off
.LBB0_35:
	s_or_b64 exec, exec, s[50:51]
	s_add_i32 s48, s63, s65
	s_ashr_i32 s49, s48, 31
	s_lshr_b32 s49, s49, 28
	s_add_i32 s49, s48, s49
	s_and_b32 s50, s49, 0x3fffff0
	s_lshl_b32 s49, s49, 2
	s_sub_i32 s54, s48, s50
	s_andn2_b32 s49, s49, 63
	v_or_b32_e32 v16, s49, v39
	s_cmpk_lt_i32 s48, 0x240
	s_cselect_b64 s[50:51], -1, 0
	v_cmp_gt_i32_e32 vcc, s78, v16
	v_ashrrev_i32_e32 v17, 31, v16
	s_and_b64 s[52:53], s[50:51], vcc
	s_lshl_b32 s48, s54, 6
	v_lshl_add_u64 v[24:25], v[16:17], 2, s[42:43]
	v_mov_b32_e32 v16, 0
	v_mov_b32_e32 v20, 0
	v_mov_b32_e32 v21, 0
	v_mov_b32_e32 v22, 0
	v_mov_b32_e32 v23, 0
	s_and_saveexec_b64 s[54:55], s[52:53]
	s_cbranch_execz .LBB0_38
	v_add_u32_e32 v18, s48, v42
	v_mad_i64_i32 v[20:21], s[56:57], v18, s79, v[24:25]
	global_load_dwordx4 v[20:23], v[20:21], off
	s_and_b64 vcc, exec, s[2:3]
	s_cbranch_vccnz .LBB0_38
	v_ashrrev_i32_e32 v19, 31, v18
	v_lshl_add_u64 v[18:19], v[18:19], 2, s[40:41]
	global_load_dword v68, v[18:19], off
.LBB0_38:
	s_or_b64 exec, exec, s[54:55]
	v_mov_b32_e32 v17, 0
	v_mov_b32_e32 v18, 0
	v_mov_b32_e32 v19, 0
	s_and_saveexec_b64 s[54:55], s[52:53]
	s_cbranch_execz .LBB0_41
	v_add_u32_e32 v26, s48, v43
	v_mad_i64_i32 v[16:17], s[52:53], v26, s79, v[24:25]
	global_load_dwordx4 v[16:19], v[16:17], off
	s_and_b64 vcc, exec, s[2:3]
	s_cbranch_vccnz .LBB0_41
	v_ashrrev_i32_e32 v27, 31, v26
	v_lshl_add_u64 v[24:25], v[26:27], 2, s[40:41]
	global_load_dword v70, v[24:25], off
; DI void prep_wt(const float* __restrict__ src, u16* __restrict__ dst, int K, int N, int Npad,
;                 const float* __restrict__ gain, float* tile) {
;     ...
;         const int e = tid + NTHR * i; const int kk = e >> 4, n4 = (e & 15) * 4; const int n = nt * 64 + n4;
;         v[j][i] = (f32x4){0.f, 0.f, 0.f, 0.f};
;         if (t < nt4 && n < N) {
;           v[j][i] = *(const f32x4*)(src + (size_t)(kt * 64 + kk) * N + n);
;           if (gain) v[j][i] *= gain[kt * 64 + kk];
;         }
;       }
;     }
;     __syncthreads();
; #pragma unroll
;     for (int j = 0; j < 4; ++j)
; #pragma unroll
;       for (int i = 0; i < 2; ++i) {
;         const int e = tid + NTHR * i; const int kk = e >> 4, n4 = (e & 15) * 4;
;         float* tp = tile + j * TS + kk * 65 + n4;
;         tp[0] = v[j][i][0]; tp[1] = v[j][i][1]; tp[2] = v[j][i][2]; tp[3] = v[j][i][3];
;       }
;     __syncthreads();
; #pragma unroll
;     for (int j = 0; j < 4; ++j) {
;       const int t = t0 + j * gridDim.x;
;       if (t < nt4) {
;         const int kt = t % tk, nt = t / tk;
;         const int nn = tid >> 3, k8 = (tid & 7) * 8;
;         const float* tp = tile + j * TS + k8 * 65 + nn;
;         u32x4 u;
;         u.x = pack2(tp[0 * 65], tp[1 * 65]); u.y = pack2(tp[2 * 65], tp[3 * 65]);
;         u.z = pack2(tp[4 * 65], tp[5 * 65]); u.w = pack2(tp[6 * 65], tp[7 * 65]);
;         *(u32x4*)(dst + (size_t)(nt * 64 + nn) * K + kt * 64 + k8) = u;
.LBB0_41:
	s_or_b64 exec, exec, s[54:55]
	s_mul_i32 s52, s60, 3
	s_add_i32 s52, s52, s65
	s_ashr_i32 s53, s52, 31
	s_lshr_b32 s53, s53, 28
	s_add_i32 s53, s52, s53
	s_and_b32 s54, s53, 0x3fffff0
	s_lshl_b32 s53, s53, 2
	s_sub_i32 s58, s52, s54
	s_andn2_b32 s53, s53, 63
	v_or_b32_e32 v24, s53, v39
	s_cmpk_lt_i32 s52, 0x240
	s_cselect_b64 s[54:55], -1, 0
	v_cmp_gt_i32_e32 vcc, s78, v24
	v_ashrrev_i32_e32 v25, 31, v24
	s_and_b64 s[56:57], s[54:55], vcc
	s_lshl_b32 s52, s58, 6
	v_lshl_add_u64 v[34:35], v[24:25], 2, s[42:43]
	v_mov_b32_e32 v24, 0
	v_mov_b32_e32 v28, 0
	v_mov_b32_e32 v29, 0
	v_mov_b32_e32 v30, 0
	v_mov_b32_e32 v31, 0
	s_and_saveexec_b64 s[58:59], s[56:57]
	s_cbranch_execz .LBB0_44
	v_add_u32_e32 v26, s52, v42
	v_mad_i64_i32 v[28:29], s[86:87], v26, s79, v[34:35]
	global_load_dwordx4 v[28:31], v[28:29], off
	s_and_b64 vcc, exec, s[2:3]
	s_cbranch_vccnz .LBB0_44
	v_ashrrev_i32_e32 v27, 31, v26
	v_lshl_add_u64 v[26:27], v[26:27], 2, s[40:41]
	global_load_dword v72, v[26:27], off
.LBB0_44:
	s_or_b64 exec, exec, s[58:59]
	v_mov_b32_e32 v25, 0
	v_mov_b32_e32 v26, 0
	v_mov_b32_e32 v27, 0
	s_and_saveexec_b64 s[58:59], s[56:57]
	s_cbranch_execz .LBB0_47
	v_add_u32_e32 v36, s52, v43
	v_mad_i64_i32 v[24:25], s[56:57], v36, s79, v[34:35]
	global_load_dwordx4 v[24:27], v[24:25], off
	s_and_b64 vcc, exec, s[2:3]
	s_cbranch_vccnz .LBB0_47
	v_ashrrev_i32_e32 v37, 31, v36
	v_lshl_add_u64 v[34:35], v[36:37], 2, s[40:41]
	global_load_dword v74, v[34:35], off
.LBB0_47:
	s_or_b64 exec, exec, s[58:59]
	s_barrier
	s_waitcnt vmcnt(0)
	v_pk_mul_f32 v[6:7], v[6:7], v[60:61] op_sel_hi:[1,0]
	v_pk_mul_f32 v[4:5], v[4:5], v[60:61] op_sel_hi:[1,0]
	v_pk_mul_f32 v[2:3], v[2:3], v[62:63] op_sel_hi:[1,0]
	v_pk_mul_f32 v[0:1], v[0:1], v[62:63] op_sel_hi:[1,0]
	v_pk_mul_f32 v[14:15], v[14:15], v[64:65] op_sel_hi:[1,0]
	v_pk_mul_f32 v[12:13], v[12:13], v[64:65] op_sel_hi:[1,0]
	v_pk_mul_f32 v[10:11], v[10:11], v[66:67] op_sel_hi:[1,0]
	v_pk_mul_f32 v[8:9], v[8:9], v[66:67] op_sel_hi:[1,0]
	v_pk_mul_f32 v[22:23], v[22:23], v[68:69] op_sel_hi:[1,0]
	v_pk_mul_f32 v[20:21], v[20:21], v[68:69] op_sel_hi:[1,0]
	v_pk_mul_f32 v[18:19], v[18:19], v[70:71] op_sel_hi:[1,0]
	v_pk_mul_f32 v[16:17], v[16:17], v[70:71] op_sel_hi:[1,0]
	v_pk_mul_f32 v[30:31], v[30:31], v[72:73] op_sel_hi:[1,0]
	v_pk_mul_f32 v[28:29], v[28:29], v[72:73] op_sel_hi:[1,0]
	v_pk_mul_f32 v[26:27], v[26:27], v[74:75] op_sel_hi:[1,0]
	v_pk_mul_f32 v[24:25], v[24:25], v[74:75] op_sel_hi:[1,0]
	ds_write2_b32 v44, v4, v5 offset1:1
	ds_write2_b32 v44, v6, v7 offset0:2 offset1:3
	ds_write2_b32 v45, v0, v1 offset1:1
	ds_write2_b32 v45, v2, v3 offset0:2 offset1:3
	v_add_u32_e32 v0, 0x4100, v44
	ds_write2_b32 v0, v12, v13 offset1:1
	v_add_u32_e32 v0, 0x4108, v44
	ds_write2_b32 v0, v14, v15 offset1:1
	v_add_u32_e32 v0, 0x4100, v45
	ds_write2_b32 v0, v8, v9 offset1:1
	v_add_u32_e32 v0, 0x4108, v45
	ds_write2_b32 v0, v10, v11 offset1:1
	v_add_u32_e32 v0, 0x8200, v44
	ds_write2_b32 v0, v20, v21 offset1:1
	v_add_u32_e32 v0, 0x8208, v44
	ds_write2_b32 v0, v22, v23 offset1:1
	v_add_u32_e32 v0, 0x8200, v45
	ds_write2_b32 v0, v16, v17 offset1:1
	v_add_u32_e32 v0, 0x8208, v45
	ds_write2_b32 v0, v18, v19 offset1:1
	v_add_u32_e32 v0, 0xc300, v44
	ds_write2_b32 v0, v28, v29 offset1:1
	v_add_u32_e32 v0, 0xc308, v44
	ds_write2_b32 v0, v30, v31 offset1:1
	v_add_u32_e32 v0, 0xc300, v45
	ds_write2_b32 v0, v24, v25 offset1:1
	v_add_u32_e32 v0, 0xc308, v45
	ds_write2_b32 v0, v26, v27 offset1:1
	s_waitcnt lgkmcnt(0)
	s_barrier
	ds_read2_b32 v[0:1], v41 offset1:65
	ds_read2_b32 v[2:3], v41 offset0:130 offset1:195
	v_add_u32_e32 v6, 0x400, v41
	ds_read2_b32 v[4:5], v6 offset0:4 offset1:69
	ds_read2_b32 v[6:7], v6 offset0:134 offset1:199
	s_add_i32 s2, s64, s84
	s_waitcnt lgkmcnt(3)
	v_cvt_pk_bf16_f32 v0, v0, v1
	s_waitcnt lgkmcnt(2)
	v_cvt_pk_bf16_f32 v1, v2, v3
	s_waitcnt lgkmcnt(1)
	v_cvt_pk_bf16_f32 v2, v4, v5
	v_add_u32_e32 v4, s83, v40
	v_ashrrev_i32_e32 v5, 31, v4
	v_lshlrev_b64 v[4:5], 11, v[4:5]
	v_lshl_add_u64 v[4:5], s[44:45], 0, v[4:5]
	s_ashr_i32 s3, s2, 31
	v_lshl_add_u64 v[4:5], s[2:3], 1, v[4:5]
	s_waitcnt lgkmcnt(0)
	v_cvt_pk_bf16_f32 v3, v6, v7
	v_lshl_add_u64 v[4:5], v[4:5], 0, v[32:33]
	s_andn2_b64 vcc, exec, s[46:47]
	global_store_dwordx4 v[4:5], v[0:3], off
	s_cbranch_vccz .LBB0_50
	s_andn2_b64 vcc, exec, s[50:51]
	s_cbranch_vccz .LBB0_51

; DI void prep_wt(const float* __restrict__ src, u16* __restrict__ dst, int K, int N, int Npad,
;                 const float* __restrict__ gain, float* tile) {
;     ...
;   for (int t0 = blockIdx.x; t0 < nt4; t0 += 4 * gridDim.x) {
;     f32x4 v[4][2];
; #pragma unroll
;     for (int j = 0; j < 4; ++j) {
;       const int t = t0 + j * gridDim.x;
;       const int kt = t % tk, nt = t / tk;
; #pragma unroll
;       for (int i = 0; i < 2; ++i) {
;         const int e = tid + NTHR * i; const int kk = e >> 4, n4 = (e & 15) * 4; const int n = nt * 64 + n4;
;         v[j][i] = (f32x4){0.f, 0.f, 0.f, 0.f};
;         if (t < nt4 && n < N) {
;           v[j][i] = *(const f32x4*)(src + (size_t)(kt * 64 + kk) * N + n);
;           if (gain) v[j][i] *= gain[kt * 64 + kk];
;         }
;       }
;     }
.LBB0_56:
	s_mul_hi_i32 s0, s84, 0x2aaaaaab
	s_lshr_b32 s1, s0, 31
	s_add_i32 s86, s0, s1
	s_lshl_b32 s85, s86, 6
	v_or_b32_e32 v0, s85, v39
	v_ashrrev_i32_e32 v1, 31, v0
	v_lshl_add_u64 v[8:9], v[0:1], 2, s[42:43]
	v_cndmask_b32_e64 v1, 0, 1, s[30:31]
	v_cmp_gt_i32_e64 s[0:1], s72, v0
	s_mulk_i32 s86, 0xfe80
	v_mov_b32_e32 v0, 0
	v_cmp_ne_u32_e64 s[2:3], 1, v1
	v_mov_b32_e32 v4, 0
	v_mov_b32_e32 v5, 0
	v_mov_b32_e32 v6, 0
	v_mov_b32_e32 v7, 0
	v_mov_b32_e32 v60, 1.0
	v_mov_b32_e32 v62, 1.0
	v_mov_b32_e32 v64, 1.0
	v_mov_b32_e32 v66, 1.0
	v_mov_b32_e32 v68, 1.0
	v_mov_b32_e32 v70, 1.0
	v_mov_b32_e32 v72, 1.0
	v_mov_b32_e32 v74, 1.0
	s_and_saveexec_b64 s[48:49], s[0:1]
	s_cbranch_execz .LBB0_59
	s_add_i32 s50, s86, s83
	v_add_u32_e32 v2, s50, v42
	v_mad_i64_i32 v[4:5], s[50:51], v2, s80, v[8:9]
	global_load_dwordx4 v[4:7], v[4:5], off
	s_and_b64 vcc, exec, s[2:3]
	s_cbranch_vccnz .LBB0_59
	v_ashrrev_i32_e32 v3, 31, v2
	v_lshl_add_u64 v[2:3], v[2:3], 2, s[46:47]
	global_load_dword v60, v[2:3], off
.LBB0_59:
	s_or_b64 exec, exec, s[48:49]
	v_mov_b32_e32 v1, 0
	v_mov_b32_e32 v2, 0
	v_mov_b32_e32 v3, 0
	s_and_saveexec_b64 s[48:49], s[0:1]
	s_cbranch_execz .LBB0_62
	s_add_i32 s0, s86, s83
	v_add_u32_e32 v10, s0, v43
	v_mad_i64_i32 v[0:1], s[0:1], v10, s80, v[8:9]
	global_load_dwordx4 v[0:3], v[0:1], off
	s_and_b64 vcc, exec, s[2:3]
	s_cbranch_vccnz .LBB0_62
	v_ashrrev_i32_e32 v11, 31, v10
	v_lshl_add_u64 v[8:9], v[10:11], 2, s[46:47]
	global_load_dword v62, v[8:9], off
.LBB0_62:
	s_or_b64 exec, exec, s[48:49]
	s_add_i32 s0, s62, s84
	s_mul_hi_i32 s1, s0, 0x2aaaaaab
	s_lshr_b32 s48, s1, 31
	s_add_i32 s1, s1, s48
	s_mul_i32 s48, s1, 6
	s_sub_i32 s52, s0, s48
	s_lshl_b32 s1, s1, 6
	v_or_b32_e32 v8, s1, v39
	s_cmpk_lt_i32 s0, 0x48
	s_cselect_b64 s[48:49], -1, 0
	v_cmp_gt_i32_e32 vcc, s72, v8
	v_ashrrev_i32_e32 v9, 31, v8
	s_and_b64 s[50:51], s[48:49], vcc
	s_lshl_b32 s0, s52, 6
	v_lshl_add_u64 v[16:17], v[8:9], 2, s[42:43]
	v_mov_b32_e32 v8, 0
	v_mov_b32_e32 v12, 0
	v_mov_b32_e32 v13, 0
	v_mov_b32_e32 v14, 0
	v_mov_b32_e32 v15, 0
	s_and_saveexec_b64 s[52:53], s[50:51]
	s_cbranch_execz .LBB0_65
	v_add_u32_e32 v10, s0, v42
	v_mad_i64_i32 v[12:13], s[54:55], v10, s80, v[16:17]
	global_load_dwordx4 v[12:15], v[12:13], off
	s_and_b64 vcc, exec, s[2:3]
	s_cbranch_vccnz .LBB0_65
	v_ashrrev_i32_e32 v11, 31, v10
	v_lshl_add_u64 v[10:11], v[10:11], 2, s[46:47]
	global_load_dword v64, v[10:11], off
.LBB0_65:
	s_or_b64 exec, exec, s[52:53]
	v_mov_b32_e32 v9, 0
	v_mov_b32_e32 v10, 0
	v_mov_b32_e32 v11, 0
	s_and_saveexec_b64 s[52:53], s[50:51]
	s_cbranch_execz .LBB0_68
	v_add_u32_e32 v18, s0, v43
	v_mad_i64_i32 v[8:9], s[50:51], v18, s80, v[16:17]
	global_load_dwordx4 v[8:11], v[8:9], off
	s_and_b64 vcc, exec, s[2:3]
	s_cbranch_vccnz .LBB0_68
	v_ashrrev_i32_e32 v19, 31, v18
	v_lshl_add_u64 v[16:17], v[18:19], 2, s[46:47]
	global_load_dword v66, v[16:17], off
.LBB0_68:
	s_or_b64 exec, exec, s[52:53]
	s_add_i32 s50, s65, s84
	s_mul_hi_i32 s51, s50, 0x2aaaaaab
	s_lshr_b32 s52, s51, 31
	s_add_i32 s51, s51, s52
	s_mul_i32 s52, s51, 6
	s_sub_i32 s56, s50, s52
	s_lshl_b32 s51, s51, 6
	v_or_b32_e32 v16, s51, v39
	s_cmpk_lt_i32 s50, 0x48
	s_cselect_b64 s[52:53], -1, 0
	v_cmp_gt_i32_e32 vcc, s72, v16
	v_ashrrev_i32_e32 v17, 31, v16
	s_and_b64 s[54:55], s[52:53], vcc
	s_lshl_b32 s50, s56, 6
	v_lshl_add_u64 v[24:25], v[16:17], 2, s[42:43]
	v_mov_b32_e32 v16, 0
	v_mov_b32_e32 v20, 0
	v_mov_b32_e32 v21, 0
	v_mov_b32_e32 v22, 0
	v_mov_b32_e32 v23, 0
	s_and_saveexec_b64 s[56:57], s[54:55]
	s_cbranch_execz .LBB0_71
	v_add_u32_e32 v18, s50, v42
	v_mad_i64_i32 v[20:21], s[58:59], v18, s80, v[24:25]
	global_load_dwordx4 v[20:23], v[20:21], off
	s_and_b64 vcc, exec, s[2:3]
	s_cbranch_vccnz .LBB0_71
	v_ashrrev_i32_e32 v19, 31, v18
	v_lshl_add_u64 v[18:19], v[18:19], 2, s[46:47]
	global_load_dword v68, v[18:19], off
.LBB0_71:
	s_or_b64 exec, exec, s[56:57]
	v_mov_b32_e32 v17, 0
	v_mov_b32_e32 v18, 0
	v_mov_b32_e32 v19, 0
	s_and_saveexec_b64 s[56:57], s[54:55]
	s_cbranch_execz .LBB0_74
	v_add_u32_e32 v26, s50, v43
	v_mad_i64_i32 v[16:17], s[54:55], v26, s80, v[24:25]
	global_load_dwordx4 v[16:19], v[16:17], off
	s_and_b64 vcc, exec, s[2:3]
	s_cbranch_vccnz .LBB0_74
	v_ashrrev_i32_e32 v27, 31, v26
	v_lshl_add_u64 v[24:25], v[26:27], 2, s[46:47]
	global_load_dword v70, v[24:25], off
; DI void prep_wt(const float* __restrict__ src, u16* __restrict__ dst, int K, int N, int Npad,
;                 const float* __restrict__ gain, float* tile) {
;     ...
;         const int e = tid + NTHR * i; const int kk = e >> 4, n4 = (e & 15) * 4; const int n = nt * 64 + n4;
;         v[j][i] = (f32x4){0.f, 0.f, 0.f, 0.f};
;         if (t < nt4 && n < N) {
;           v[j][i] = *(const f32x4*)(src + (size_t)(kt * 64 + kk) * N + n);
;           if (gain) v[j][i] *= gain[kt * 64 + kk];
;         }
;       }
;     }
;     __syncthreads();
; #pragma unroll
;     for (int j = 0; j < 4; ++j)
; #pragma unroll
;       for (int i = 0; i < 2; ++i) {
;         const int e = tid + NTHR * i; const int kk = e >> 4, n4 = (e & 15) * 4;
;         float* tp = tile + j * TS + kk * 65 + n4;
;         tp[0] = v[j][i][0]; tp[1] = v[j][i][1]; tp[2] = v[j][i][2]; tp[3] = v[j][i][3];
;       }
;     __syncthreads();
; #pragma unroll
;     for (int j = 0; j < 4; ++j) {
;       const int t = t0 + j * gridDim.x;
;       if (t < nt4) {
;         const int kt = t % tk, nt = t / tk;
;         const int nn = tid >> 3, k8 = (tid & 7) * 8;
;         const float* tp = tile + j * TS + k8 * 65 + nn;
;         u32x4 u;
;         u.x = pack2(tp[0 * 65], tp[1 * 65]); u.y = pack2(tp[2 * 65], tp[3 * 65]);
;         u.z = pack2(tp[4 * 65], tp[5 * 65]); u.w = pack2(tp[6 * 65], tp[7 * 65]);
;         *(u32x4*)(dst + (size_t)(nt * 64 + nn) * K + kt * 64 + k8) = u;
.LBB0_74:
	s_or_b64 exec, exec, s[56:57]
	s_mul_i32 s54, s62, 3
	s_add_i32 s54, s54, s84
	s_mul_hi_i32 s55, s54, 0x2aaaaaab
	s_lshr_b32 s56, s55, 31
	s_add_i32 s55, s55, s56
	s_mul_i32 s56, s55, 6
	s_sub_i32 s60, s54, s56
	s_lshl_b32 s55, s55, 6
	v_or_b32_e32 v24, s55, v39
	s_cmpk_lt_i32 s54, 0x48
	s_cselect_b64 s[56:57], -1, 0
	v_cmp_gt_i32_e32 vcc, s72, v24
	v_ashrrev_i32_e32 v25, 31, v24
	s_and_b64 s[58:59], s[56:57], vcc
	s_lshl_b32 s54, s60, 6
	v_lshl_add_u64 v[34:35], v[24:25], 2, s[42:43]
	v_mov_b32_e32 v24, 0
	v_mov_b32_e32 v28, 0
	v_mov_b32_e32 v29, 0
	v_mov_b32_e32 v30, 0
	v_mov_b32_e32 v31, 0
	s_and_saveexec_b64 s[60:61], s[58:59]
	s_cbranch_execz .LBB0_77
	v_add_u32_e32 v26, s54, v42
	v_mad_i64_i32 v[28:29], s[88:89], v26, s80, v[34:35]
	global_load_dwordx4 v[28:31], v[28:29], off
	s_and_b64 vcc, exec, s[2:3]
	s_cbranch_vccnz .LBB0_77
	v_ashrrev_i32_e32 v27, 31, v26
	v_lshl_add_u64 v[26:27], v[26:27], 2, s[46:47]
	global_load_dword v72, v[26:27], off
.LBB0_77:
	s_or_b64 exec, exec, s[60:61]
	v_mov_b32_e32 v25, 0
	v_mov_b32_e32 v26, 0
	v_mov_b32_e32 v27, 0
	s_and_saveexec_b64 s[60:61], s[58:59]
	s_cbranch_execz .LBB0_80
	v_add_u32_e32 v36, s54, v43
	v_mad_i64_i32 v[24:25], s[58:59], v36, s80, v[34:35]
	global_load_dwordx4 v[24:27], v[24:25], off
	s_and_b64 vcc, exec, s[2:3]
	s_cbranch_vccnz .LBB0_80
	v_ashrrev_i32_e32 v37, 31, v36
	v_lshl_add_u64 v[34:35], v[36:37], 2, s[46:47]
	global_load_dword v74, v[34:35], off
.LBB0_80:
	s_or_b64 exec, exec, s[60:61]
	s_barrier
	s_waitcnt vmcnt(0)
	v_pk_mul_f32 v[6:7], v[6:7], v[60:61] op_sel_hi:[1,0]
	v_pk_mul_f32 v[4:5], v[4:5], v[60:61] op_sel_hi:[1,0]
	v_pk_mul_f32 v[2:3], v[2:3], v[62:63] op_sel_hi:[1,0]
	v_pk_mul_f32 v[0:1], v[0:1], v[62:63] op_sel_hi:[1,0]
	v_pk_mul_f32 v[14:15], v[14:15], v[64:65] op_sel_hi:[1,0]
	v_pk_mul_f32 v[12:13], v[12:13], v[64:65] op_sel_hi:[1,0]
	v_pk_mul_f32 v[10:11], v[10:11], v[66:67] op_sel_hi:[1,0]
	v_pk_mul_f32 v[8:9], v[8:9], v[66:67] op_sel_hi:[1,0]
	v_pk_mul_f32 v[22:23], v[22:23], v[68:69] op_sel_hi:[1,0]
	v_pk_mul_f32 v[20:21], v[20:21], v[68:69] op_sel_hi:[1,0]
	v_pk_mul_f32 v[18:19], v[18:19], v[70:71] op_sel_hi:[1,0]
	v_pk_mul_f32 v[16:17], v[16:17], v[70:71] op_sel_hi:[1,0]
	v_pk_mul_f32 v[30:31], v[30:31], v[72:73] op_sel_hi:[1,0]
	v_pk_mul_f32 v[28:29], v[28:29], v[72:73] op_sel_hi:[1,0]
	v_pk_mul_f32 v[26:27], v[26:27], v[74:75] op_sel_hi:[1,0]
	v_pk_mul_f32 v[24:25], v[24:25], v[74:75] op_sel_hi:[1,0]
	ds_write2_b32 v44, v4, v5 offset1:1
	ds_write2_b32 v44, v6, v7 offset0:2 offset1:3
	ds_write2_b32 v45, v0, v1 offset1:1
	ds_write2_b32 v45, v2, v3 offset0:2 offset1:3
	v_add_u32_e32 v0, 0x4100, v44
	ds_write2_b32 v0, v12, v13 offset1:1
	v_add_u32_e32 v0, 0x4108, v44
	ds_write2_b32 v0, v14, v15 offset1:1
	v_add_u32_e32 v0, 0x4100, v45
	ds_write2_b32 v0, v8, v9 offset1:1
	v_add_u32_e32 v0, 0x4108, v45
	ds_write2_b32 v0, v10, v11 offset1:1
	v_add_u32_e32 v0, 0x8200, v44
	ds_write2_b32 v0, v20, v21 offset1:1
	v_add_u32_e32 v0, 0x8208, v44
	ds_write2_b32 v0, v22, v23 offset1:1
	v_add_u32_e32 v0, 0x8200, v45
	ds_write2_b32 v0, v16, v17 offset1:1
	v_add_u32_e32 v0, 0x8208, v45
	ds_write2_b32 v0, v18, v19 offset1:1
	v_add_u32_e32 v0, 0xc300, v44
	ds_write2_b32 v0, v28, v29 offset1:1
	v_add_u32_e32 v0, 0xc308, v44
	ds_write2_b32 v0, v30, v31 offset1:1
	v_add_u32_e32 v0, 0xc300, v45
	ds_write2_b32 v0, v24, v25 offset1:1
	v_add_u32_e32 v0, 0xc308, v45
	v_add_u32_e32 v6, 0x400, v41
	ds_write2_b32 v0, v26, v27 offset1:1
	s_waitcnt lgkmcnt(0)
	s_barrier
	ds_read2_b32 v[0:1], v41 offset1:65
	ds_read2_b32 v[2:3], v41 offset0:130 offset1:195
	ds_read2_b32 v[4:5], v6 offset0:4 offset1:69
	ds_read2_b32 v[6:7], v6 offset0:134 offset1:199
	s_add_i32 s2, s83, s86
	s_ashr_i32 s3, s2, 31
	s_waitcnt lgkmcnt(3)
	v_cvt_pk_bf16_f32 v0, v0, v1
	s_waitcnt lgkmcnt(2)
	v_cvt_pk_bf16_f32 v1, v2, v3
	s_waitcnt lgkmcnt(1)
	v_cvt_pk_bf16_f32 v2, v4, v5
	s_waitcnt lgkmcnt(0)
	v_cvt_pk_bf16_f32 v3, v6, v7
	v_add_u32_e32 v6, s85, v40
	v_mov_b64_e32 v[4:5], s[44:45]
	v_mad_i64_i32 v[4:5], s[58:59], v6, s72, v[4:5]
	v_lshl_add_u64 v[4:5], s[2:3], 1, v[4:5]
	v_lshl_add_u64 v[4:5], v[4:5], 0, v[32:33]
	s_andn2_b64 vcc, exec, s[48:49]
	global_store_dwordx4 v[4:5], v[0:3], off
	s_cbranch_vccz .LBB0_83
	s_andn2_b64 vcc, exec, s[52:53]
	s_cbranch_vccz .LBB0_84

; DI void prep_wt(const float* __restrict__ src, u16* __restrict__ dst, int K, int N, int Npad,
;                 const float* __restrict__ gain, float* tile) {
;     ...
;   for (int t0 = blockIdx.x; t0 < nt4; t0 += 4 * gridDim.x) {
;     f32x4 v[4][2];
; #pragma unroll
;     for (int j = 0; j < 4; ++j) {
;       const int t = t0 + j * gridDim.x;
;       const int kt = t % tk, nt = t / tk;
; #pragma unroll
;       for (int i = 0; i < 2; ++i) {
;         const int e = tid + NTHR * i; const int kk = e >> 4, n4 = (e & 15) * 4; const int n = nt * 64 + n4;
;         v[j][i] = (f32x4){0.f, 0.f, 0.f, 0.f};
;         if (t < nt4 && n < N) {
;           v[j][i] = *(const f32x4*)(src + (size_t)(kt * 64 + kk) * N + n);
;           if (gain) v[j][i] *= gain[kt * 64 + kk];
;         }
;       }
;     }
.LBB0_89:
	s_ashr_i32 s0, s54, 31
	s_lshr_b32 s0, s0, 30
	s_add_i32 s0, s54, s0
	s_lshl_b32 s51, s0, 4
	s_andn2_b32 s51, s51, 63
	v_or_b32_e32 v0, s51, v39
	s_and_b32 s1, s0, 0x3fffffc
	v_ashrrev_i32_e32 v1, 31, v0
	s_sub_i32 s2, s54, s1
	v_lshl_add_u64 v[8:9], v[0:1], 2, s[44:45]
	v_cndmask_b32_e64 v1, 0, 1, s[34:35]
	v_cmp_gt_i32_e64 s[0:1], s81, v0
	s_lshl_b32 s50, s2, 6
	v_mov_b32_e32 v0, 0
	v_cmp_ne_u32_e64 s[2:3], 1, v1
	v_mov_b32_e32 v4, 0
	v_mov_b32_e32 v5, 0
	v_mov_b32_e32 v6, 0
	v_mov_b32_e32 v7, 0
	v_mov_b32_e32 v60, 1.0
	v_mov_b32_e32 v62, 1.0
	v_mov_b32_e32 v64, 1.0
	v_mov_b32_e32 v66, 1.0
	v_mov_b32_e32 v68, 1.0
	v_mov_b32_e32 v70, 1.0
	v_mov_b32_e32 v72, 1.0
	v_mov_b32_e32 v74, 1.0
	s_and_saveexec_b64 s[52:53], s[0:1]
	s_cbranch_execz .LBB0_92
	v_add_u32_e32 v2, s50, v42
	v_ashrrev_i32_e32 v3, 31, v2
	v_lshlrev_b64 v[4:5], 12, v[2:3]
	v_lshl_add_u64 v[4:5], v[8:9], 0, v[4:5]
	global_load_dwordx4 v[4:7], v[4:5], off
	s_and_b64 vcc, exec, s[2:3]
	s_cbranch_vccnz .LBB0_92
	v_lshl_add_u64 v[2:3], v[2:3], 2, s[48:49]
	global_load_dword v60, v[2:3], off
.LBB0_92:
	s_or_b64 exec, exec, s[52:53]
	v_mov_b32_e32 v1, 0
	v_mov_b32_e32 v2, 0
	v_mov_b32_e32 v3, 0
	s_and_saveexec_b64 s[52:53], s[0:1]
	s_cbranch_execz .LBB0_95
	v_add_u32_e32 v10, s50, v43
	v_ashrrev_i32_e32 v11, 31, v10
	v_lshlrev_b64 v[0:1], 12, v[10:11]
	v_lshl_add_u64 v[0:1], v[8:9], 0, v[0:1]
	global_load_dwordx4 v[0:3], v[0:1], off
	s_and_b64 vcc, exec, s[2:3]
	s_cbranch_vccnz .LBB0_95
	v_lshl_add_u64 v[8:9], v[10:11], 2, s[48:49]
	global_load_dword v62, v[8:9], off
.LBB0_95:
	s_or_b64 exec, exec, s[52:53]
	s_add_i32 s58, s83, s54
	s_ashr_i32 s0, s58, 31
	s_lshr_b32 s0, s0, 30
	s_add_i32 s0, s58, s0
	s_and_b32 s1, s0, 0x3fffffc
	s_sub_i32 s56, s58, s1
	s_lshl_b32 s1, s0, 4
	s_andn2_b32 s1, s1, 63
	v_or_b32_e32 v8, s1, v39
	s_cmp_lt_i32 s58, 64
	s_cselect_b64 s[52:53], -1, 0
	v_cmp_gt_i32_e32 vcc, s81, v8
	v_ashrrev_i32_e32 v9, 31, v8
	s_and_b64 s[54:55], s[52:53], vcc
	s_lshl_b32 s0, s56, 6
	v_lshl_add_u64 v[16:17], v[8:9], 2, s[44:45]
	v_mov_b32_e32 v8, 0
	v_mov_b32_e32 v12, 0
	v_mov_b32_e32 v13, 0
	v_mov_b32_e32 v14, 0
	v_mov_b32_e32 v15, 0
	s_and_saveexec_b64 s[56:57], s[54:55]
	s_cbranch_execz .LBB0_98
	v_add_u32_e32 v10, s0, v42
	v_ashrrev_i32_e32 v11, 31, v10
	v_lshlrev_b64 v[12:13], 12, v[10:11]
	v_lshl_add_u64 v[12:13], v[16:17], 0, v[12:13]
	global_load_dwordx4 v[12:15], v[12:13], off
	s_and_b64 vcc, exec, s[2:3]
	s_cbranch_vccnz .LBB0_98
	v_lshl_add_u64 v[10:11], v[10:11], 2, s[48:49]
	global_load_dword v64, v[10:11], off
.LBB0_98:
	s_or_b64 exec, exec, s[56:57]
	v_mov_b32_e32 v9, 0
	v_mov_b32_e32 v10, 0
	v_mov_b32_e32 v11, 0
	s_and_saveexec_b64 s[56:57], s[54:55]
	s_cbranch_execz .LBB0_101
	v_add_u32_e32 v18, s0, v43
	v_ashrrev_i32_e32 v19, 31, v18
	v_lshlrev_b64 v[8:9], 12, v[18:19]
	v_lshl_add_u64 v[8:9], v[16:17], 0, v[8:9]
	global_load_dwordx4 v[8:11], v[8:9], off
	s_and_b64 vcc, exec, s[2:3]
	s_cbranch_vccnz .LBB0_101
	v_lshl_add_u64 v[16:17], v[18:19], 2, s[48:49]
	global_load_dword v66, v[16:17], off
.LBB0_101:
	s_or_b64 exec, exec, s[56:57]
	s_add_i32 s62, s83, s58
	s_ashr_i32 s54, s62, 31
	s_lshr_b32 s54, s54, 30
	s_add_i32 s54, s62, s54
	s_and_b32 s55, s54, 0x3fffffc
	s_sub_i32 s60, s62, s55
	s_lshl_b32 s55, s54, 4
	s_andn2_b32 s55, s55, 63
	v_or_b32_e32 v16, s55, v39
	s_cmp_lt_i32 s62, 64
	s_cselect_b64 s[56:57], -1, 0
	v_cmp_gt_i32_e32 vcc, s81, v16
	v_ashrrev_i32_e32 v17, 31, v16
	s_and_b64 s[58:59], s[56:57], vcc
	s_lshl_b32 s54, s60, 6
	v_lshl_add_u64 v[24:25], v[16:17], 2, s[44:45]
	v_mov_b32_e32 v16, 0
	v_mov_b32_e32 v20, 0
	v_mov_b32_e32 v21, 0
	v_mov_b32_e32 v22, 0
	v_mov_b32_e32 v23, 0
	s_and_saveexec_b64 s[60:61], s[58:59]
	s_cbranch_execz .LBB0_104
	v_add_u32_e32 v18, s54, v42
	v_ashrrev_i32_e32 v19, 31, v18
	v_lshlrev_b64 v[20:21], 12, v[18:19]
	v_lshl_add_u64 v[20:21], v[24:25], 0, v[20:21]
	global_load_dwordx4 v[20:23], v[20:21], off
	s_and_b64 vcc, exec, s[2:3]
	s_cbranch_vccnz .LBB0_104
	v_lshl_add_u64 v[18:19], v[18:19], 2, s[48:49]
	global_load_dword v68, v[18:19], off
.LBB0_104:
	s_or_b64 exec, exec, s[60:61]
	v_mov_b32_e32 v17, 0
	v_mov_b32_e32 v18, 0
	v_mov_b32_e32 v19, 0
	s_and_saveexec_b64 s[60:61], s[58:59]
	s_cbranch_execz .LBB0_107
	v_add_u32_e32 v26, s54, v43
	v_ashrrev_i32_e32 v27, 31, v26
	v_lshlrev_b64 v[16:17], 12, v[26:27]
	v_lshl_add_u64 v[16:17], v[24:25], 0, v[16:17]
	global_load_dwordx4 v[16:19], v[16:17], off
	s_and_b64 vcc, exec, s[2:3]
	s_cbranch_vccnz .LBB0_107
	v_lshl_add_u64 v[24:25], v[26:27], 2, s[48:49]
	global_load_dword v70, v[24:25], off
; DI void prep_wt(const float* __restrict__ src, u16* __restrict__ dst, int K, int N, int Npad,
;                 const float* __restrict__ gain, float* tile) {
;     ...
;         const int e = tid + NTHR * i; const int kk = e >> 4, n4 = (e & 15) * 4; const int n = nt * 64 + n4;
;         v[j][i] = (f32x4){0.f, 0.f, 0.f, 0.f};
;         if (t < nt4 && n < N) {
;           v[j][i] = *(const f32x4*)(src + (size_t)(kt * 64 + kk) * N + n);
;           if (gain) v[j][i] *= gain[kt * 64 + kk];
;         }
;       }
;     }
;     __syncthreads();
; #pragma unroll
;     for (int j = 0; j < 4; ++j)
; #pragma unroll
;       for (int i = 0; i < 2; ++i) {
;         const int e = tid + NTHR * i; const int kk = e >> 4, n4 = (e & 15) * 4;
;         float* tp = tile + j * TS + kk * 65 + n4;
;         tp[0] = v[j][i][0]; tp[1] = v[j][i][1]; tp[2] = v[j][i][2]; tp[3] = v[j][i][3];
;       }
;     __syncthreads();
; #pragma unroll
;     for (int j = 0; j < 4; ++j) {
;       const int t = t0 + j * gridDim.x;
;       if (t < nt4) {
;         const int kt = t % tk, nt = t / tk;
;         const int nn = tid >> 3, k8 = (tid & 7) * 8;
;         const float* tp = tile + j * TS + k8 * 65 + nn;
;         u32x4 u;
;         u.x = pack2(tp[0 * 65], tp[1 * 65]); u.y = pack2(tp[2 * 65], tp[3 * 65]);
;         u.z = pack2(tp[4 * 65], tp[5 * 65]); u.w = pack2(tp[6 * 65], tp[7 * 65]);
;         *(u32x4*)(dst + (size_t)(nt * 64 + nn) * K + kt * 64 + k8) = u;
.LBB0_107:
	s_or_b64 exec, exec, s[60:61]
	s_add_i32 s84, s83, s62
	s_ashr_i32 s58, s84, 31
	s_lshr_b32 s58, s58, 30
	s_add_i32 s58, s84, s58
	s_and_b32 s59, s58, 0x3fffffc
	s_sub_i32 s64, s84, s59
	s_lshl_b32 s59, s58, 4
	s_andn2_b32 s59, s59, 63
	v_or_b32_e32 v24, s59, v39
	s_cmp_lt_i32 s84, 64
	s_cselect_b64 s[60:61], -1, 0
	v_cmp_gt_i32_e32 vcc, s81, v24
	v_ashrrev_i32_e32 v25, 31, v24
	s_and_b64 s[62:63], s[60:61], vcc
	s_lshl_b32 s58, s64, 6
	v_lshl_add_u64 v[34:35], v[24:25], 2, s[44:45]
	v_mov_b32_e32 v24, 0
	v_mov_b32_e32 v28, 0
	v_mov_b32_e32 v29, 0
	v_mov_b32_e32 v30, 0
	v_mov_b32_e32 v31, 0
	s_and_saveexec_b64 s[64:65], s[62:63]
	s_cbranch_execz .LBB0_110
	v_add_u32_e32 v26, s58, v42
	v_ashrrev_i32_e32 v27, 31, v26
	v_lshlrev_b64 v[28:29], 12, v[26:27]
	v_lshl_add_u64 v[28:29], v[34:35], 0, v[28:29]
	global_load_dwordx4 v[28:31], v[28:29], off
	s_and_b64 vcc, exec, s[2:3]
	s_cbranch_vccnz .LBB0_110
	v_lshl_add_u64 v[26:27], v[26:27], 2, s[48:49]
	global_load_dword v72, v[26:27], off
.LBB0_110:
	s_or_b64 exec, exec, s[64:65]
	v_mov_b32_e32 v25, 0
	v_mov_b32_e32 v26, 0
	v_mov_b32_e32 v27, 0
	s_and_saveexec_b64 s[64:65], s[62:63]
	s_cbranch_execz .LBB0_113
	v_add_u32_e32 v36, s58, v43
	v_ashrrev_i32_e32 v37, 31, v36
	v_lshlrev_b64 v[24:25], 12, v[36:37]
	v_lshl_add_u64 v[24:25], v[34:35], 0, v[24:25]
	global_load_dwordx4 v[24:27], v[24:25], off
	s_and_b64 vcc, exec, s[2:3]
	s_cbranch_vccnz .LBB0_113
	v_lshl_add_u64 v[34:35], v[36:37], 2, s[48:49]
	global_load_dword v74, v[34:35], off
.LBB0_113:
	s_or_b64 exec, exec, s[64:65]
	s_barrier
	s_waitcnt vmcnt(0)
	v_pk_mul_f32 v[6:7], v[6:7], v[60:61] op_sel_hi:[1,0]
	v_pk_mul_f32 v[4:5], v[4:5], v[60:61] op_sel_hi:[1,0]
	v_pk_mul_f32 v[2:3], v[2:3], v[62:63] op_sel_hi:[1,0]
	v_pk_mul_f32 v[0:1], v[0:1], v[62:63] op_sel_hi:[1,0]
	v_pk_mul_f32 v[14:15], v[14:15], v[64:65] op_sel_hi:[1,0]
	v_pk_mul_f32 v[12:13], v[12:13], v[64:65] op_sel_hi:[1,0]
	v_pk_mul_f32 v[10:11], v[10:11], v[66:67] op_sel_hi:[1,0]
	v_pk_mul_f32 v[8:9], v[8:9], v[66:67] op_sel_hi:[1,0]
	v_pk_mul_f32 v[22:23], v[22:23], v[68:69] op_sel_hi:[1,0]
	v_pk_mul_f32 v[20:21], v[20:21], v[68:69] op_sel_hi:[1,0]
	v_pk_mul_f32 v[18:19], v[18:19], v[70:71] op_sel_hi:[1,0]
	v_pk_mul_f32 v[16:17], v[16:17], v[70:71] op_sel_hi:[1,0]
	v_pk_mul_f32 v[30:31], v[30:31], v[72:73] op_sel_hi:[1,0]
	v_pk_mul_f32 v[28:29], v[28:29], v[72:73] op_sel_hi:[1,0]
	v_pk_mul_f32 v[26:27], v[26:27], v[74:75] op_sel_hi:[1,0]
	v_pk_mul_f32 v[24:25], v[24:25], v[74:75] op_sel_hi:[1,0]
	ds_write2_b32 v44, v4, v5 offset1:1
	ds_write2_b32 v44, v6, v7 offset0:2 offset1:3
	ds_write2_b32 v45, v0, v1 offset1:1
	ds_write2_b32 v45, v2, v3 offset0:2 offset1:3
	v_add_u32_e32 v0, 0x4100, v44
	ds_write2_b32 v0, v12, v13 offset1:1
	v_add_u32_e32 v0, 0x4108, v44
	ds_write2_b32 v0, v14, v15 offset1:1
	v_add_u32_e32 v0, 0x4100, v45
	ds_write2_b32 v0, v8, v9 offset1:1
	v_add_u32_e32 v0, 0x4108, v45
	ds_write2_b32 v0, v10, v11 offset1:1
	v_add_u32_e32 v0, 0x8200, v44
	ds_write2_b32 v0, v20, v21 offset1:1
	v_add_u32_e32 v0, 0x8208, v44
	ds_write2_b32 v0, v22, v23 offset1:1
	v_add_u32_e32 v0, 0x8200, v45
	ds_write2_b32 v0, v16, v17 offset1:1
	v_add_u32_e32 v0, 0x8208, v45
	ds_write2_b32 v0, v18, v19 offset1:1
	v_add_u32_e32 v0, 0xc300, v44
	ds_write2_b32 v0, v28, v29 offset1:1
	v_add_u32_e32 v0, 0xc308, v44
	ds_write2_b32 v0, v30, v31 offset1:1
	v_add_u32_e32 v0, 0xc300, v45
	ds_write2_b32 v0, v24, v25 offset1:1
	v_add_u32_e32 v0, 0xc308, v45
	ds_write2_b32 v0, v26, v27 offset1:1
	s_waitcnt lgkmcnt(0)
	s_barrier
	ds_read2_b32 v[0:1], v41 offset1:65
	ds_read2_b32 v[2:3], v41 offset0:130 offset1:195
	v_add_u32_e32 v6, 0x400, v41
	ds_read2_b32 v[4:5], v6 offset0:4 offset1:69
	ds_read2_b32 v[6:7], v6 offset0:134 offset1:199
	s_andn2_b64 vcc, exec, s[52:53]
	s_waitcnt lgkmcnt(3)
	v_cvt_pk_bf16_f32 v0, v0, v1
	s_waitcnt lgkmcnt(2)
	v_cvt_pk_bf16_f32 v1, v2, v3
	s_waitcnt lgkmcnt(1)
	v_cvt_pk_bf16_f32 v2, v4, v5
	v_add_u32_e32 v4, s51, v40
	v_ashrrev_i32_e32 v5, 31, v4
	v_lshlrev_b64 v[4:5], 9, v[4:5]
	v_lshl_add_u64 v[4:5], s[46:47], 0, v[4:5]
	s_ashr_i32 s51, s50, 31
	v_lshl_add_u64 v[4:5], s[50:51], 1, v[4:5]
	s_waitcnt lgkmcnt(0)
	v_cvt_pk_bf16_f32 v3, v6, v7
	v_lshl_add_u64 v[4:5], v[4:5], 0, v[32:33]
	global_store_dwordx4 v[4:5], v[0:3], off
	s_cbranch_vccz .LBB0_116
	s_andn2_b64 vcc, exec, s[56:57]
	s_cbranch_vccz .LBB0_117

; DI void prep_wt(const float* __restrict__ src, u16* __restrict__ dst, int K, int N, int Npad,
;                 const float* __restrict__ gain, float* tile) {
;     ...
;   for (int t0 = blockIdx.x; t0 < nt4; t0 += 4 * gridDim.x) {
;     f32x4 v[4][2];
; #pragma unroll
;     for (int j = 0; j < 4; ++j) {
;       const int t = t0 + j * gridDim.x;
;       const int kt = t % tk, nt = t / tk;
; #pragma unroll
;       for (int i = 0; i < 2; ++i) {
;         const int e = tid + NTHR * i; const int kk = e >> 4, n4 = (e & 15) * 4; const int n = nt * 64 + n4;
;         v[j][i] = (f32x4){0.f, 0.f, 0.f, 0.f};
;         if (t < nt4 && n < N) {
;           v[j][i] = *(const f32x4*)(src + (size_t)(kt * 64 + kk) * N + n);
;           if (gain) v[j][i] *= gain[kt * 64 + kk];
;         }
;       }
;     }
.LBB0_199:
	s_ashr_i32 s0, s34, 31
	s_lshr_b32 s0, s0, 28
	s_add_i32 s0, s34, s0
	s_lshl_b32 s29, s0, 2
	s_andn2_b32 s29, s29, 63
	s_and_b32 s1, s0, 0x3fffff0
	v_or_b32_e32 v0, s29, v38
	s_sub_i32 s28, s34, s1
	v_ashrrev_i32_e32 v1, 31, v0
	v_cmp_gt_i32_e64 s[0:1], s50, v0
	s_lshl_b32 s28, s28, 6
	v_lshl_add_u64 v[8:9], v[0:1], 2, s[8:9]
	v_mov_b32_e32 v0, 0
	v_mov_b32_e32 v4, 0
	v_mov_b32_e32 v5, 0
	v_mov_b32_e32 v6, 0
	v_mov_b32_e32 v7, 0
	v_mov_b32_e32 v60, 1.0
	v_mov_b32_e32 v62, 1.0
	v_mov_b32_e32 v64, 1.0
	v_mov_b32_e32 v66, 1.0
	v_mov_b32_e32 v68, 1.0
	v_mov_b32_e32 v70, 1.0
	v_mov_b32_e32 v72, 1.0
	v_mov_b32_e32 v74, 1.0
	s_and_saveexec_b64 s[30:31], s[0:1]
	s_cbranch_execz .LBB0_202
	v_add_u32_e32 v2, s28, v41
	v_ashrrev_i32_e32 v3, 31, v2
	v_lshlrev_b64 v[4:5], 14, v[2:3]
	v_lshl_add_u64 v[4:5], v[8:9], 0, v[4:5]
	global_load_dwordx4 v[4:7], v[4:5], off
	s_and_b64 vcc, exec, s[4:5]
	s_cbranch_vccnz .LBB0_202
	v_lshl_add_u64 v[2:3], v[2:3], 2, s[22:23]
	global_load_dword v60, v[2:3], off
.LBB0_202:
	s_or_b64 exec, exec, s[30:31]
	v_mov_b32_e32 v1, 0
	v_mov_b32_e32 v2, 0
	v_mov_b32_e32 v3, 0
	s_and_saveexec_b64 s[30:31], s[0:1]
	s_cbranch_execz .LBB0_205
	v_add_u32_e32 v10, s28, v42
	v_ashrrev_i32_e32 v11, 31, v10
	v_lshlrev_b64 v[0:1], 14, v[10:11]
	v_lshl_add_u64 v[0:1], v[8:9], 0, v[0:1]
	global_load_dwordx4 v[0:3], v[0:1], off
	s_and_b64 vcc, exec, s[4:5]
	s_cbranch_vccnz .LBB0_205
	v_lshl_add_u64 v[8:9], v[10:11], 2, s[22:23]
	global_load_dword v62, v[8:9], off
.LBB0_205:
	s_or_b64 exec, exec, s[30:31]
	s_add_i32 s38, s52, s34
	s_ashr_i32 s0, s38, 31
	s_lshr_b32 s0, s0, 28
	s_add_i32 s0, s38, s0
	s_and_b32 s1, s0, 0x3fffff0
	s_sub_i32 s36, s38, s1
	s_lshl_b32 s1, s0, 2
	s_andn2_b32 s1, s1, 63
	v_or_b32_e32 v8, s1, v38
	s_cmpk_lt_i32 s38, 0x400
	s_cselect_b64 s[30:31], -1, 0
	v_cmp_gt_i32_e32 vcc, s50, v8
	v_ashrrev_i32_e32 v9, 31, v8
	s_and_b64 s[34:35], s[30:31], vcc
	s_lshl_b32 s0, s36, 6
	v_lshl_add_u64 v[16:17], v[8:9], 2, s[8:9]
	v_mov_b32_e32 v8, 0
	v_mov_b32_e32 v12, 0
	v_mov_b32_e32 v13, 0
	v_mov_b32_e32 v14, 0
	v_mov_b32_e32 v15, 0
	s_and_saveexec_b64 s[36:37], s[34:35]
	s_cbranch_execz .LBB0_208
	v_add_u32_e32 v10, s0, v41
	v_ashrrev_i32_e32 v11, 31, v10
	v_lshlrev_b64 v[12:13], 14, v[10:11]
	v_lshl_add_u64 v[12:13], v[16:17], 0, v[12:13]
	global_load_dwordx4 v[12:15], v[12:13], off
	s_and_b64 vcc, exec, s[4:5]
	s_cbranch_vccnz .LBB0_208
	v_lshl_add_u64 v[10:11], v[10:11], 2, s[22:23]
	global_load_dword v64, v[10:11], off
.LBB0_208:
	s_or_b64 exec, exec, s[36:37]
	v_mov_b32_e32 v9, 0
	v_mov_b32_e32 v10, 0
	v_mov_b32_e32 v11, 0
	s_and_saveexec_b64 s[36:37], s[34:35]
	s_cbranch_execz .LBB0_211
	v_add_u32_e32 v18, s0, v42
	v_ashrrev_i32_e32 v19, 31, v18
	v_lshlrev_b64 v[8:9], 14, v[18:19]
	v_lshl_add_u64 v[8:9], v[16:17], 0, v[8:9]
	global_load_dwordx4 v[8:11], v[8:9], off
	s_and_b64 vcc, exec, s[4:5]
	s_cbranch_vccnz .LBB0_211
	v_lshl_add_u64 v[16:17], v[18:19], 2, s[22:23]
	global_load_dword v66, v[16:17], off
.LBB0_211:
	s_or_b64 exec, exec, s[36:37]
	s_add_i32 s42, s52, s38
	s_ashr_i32 s34, s42, 31
	s_lshr_b32 s34, s34, 28
	s_add_i32 s34, s42, s34
	s_and_b32 s35, s34, 0x3fffff0
	s_sub_i32 s40, s42, s35
	s_lshl_b32 s35, s34, 2
	s_andn2_b32 s35, s35, 63
	v_or_b32_e32 v16, s35, v38
	s_cmpk_lt_i32 s42, 0x400
	s_cselect_b64 s[36:37], -1, 0
	v_cmp_gt_i32_e32 vcc, s50, v16
	v_ashrrev_i32_e32 v17, 31, v16
	s_and_b64 s[38:39], s[36:37], vcc
	s_lshl_b32 s34, s40, 6
	v_lshl_add_u64 v[24:25], v[16:17], 2, s[8:9]
	v_mov_b32_e32 v16, 0
	v_mov_b32_e32 v20, 0
	v_mov_b32_e32 v21, 0
	v_mov_b32_e32 v22, 0
	v_mov_b32_e32 v23, 0
	s_and_saveexec_b64 s[40:41], s[38:39]
	s_cbranch_execz .LBB0_214
	v_add_u32_e32 v18, s34, v41
	v_ashrrev_i32_e32 v19, 31, v18
	v_lshlrev_b64 v[20:21], 14, v[18:19]
	v_lshl_add_u64 v[20:21], v[24:25], 0, v[20:21]
	global_load_dwordx4 v[20:23], v[20:21], off
	s_and_b64 vcc, exec, s[4:5]
	s_cbranch_vccnz .LBB0_214
	v_lshl_add_u64 v[18:19], v[18:19], 2, s[22:23]
	global_load_dword v68, v[18:19], off
.LBB0_214:
	s_or_b64 exec, exec, s[40:41]
	v_mov_b32_e32 v17, 0
	v_mov_b32_e32 v18, 0
	v_mov_b32_e32 v19, 0
	s_and_saveexec_b64 s[40:41], s[38:39]
	s_cbranch_execz .LBB0_217
	v_add_u32_e32 v26, s34, v42
	v_ashrrev_i32_e32 v27, 31, v26
	v_lshlrev_b64 v[16:17], 14, v[26:27]
	v_lshl_add_u64 v[16:17], v[24:25], 0, v[16:17]
	global_load_dwordx4 v[16:19], v[16:17], off
	s_and_b64 vcc, exec, s[4:5]
	s_cbranch_vccnz .LBB0_217
	v_lshl_add_u64 v[24:25], v[26:27], 2, s[22:23]
	global_load_dword v70, v[24:25], off
; DI void prep_wt(const float* __restrict__ src, u16* __restrict__ dst, int K, int N, int Npad,
;                 const float* __restrict__ gain, float* tile) {
;     ...
;         const int e = tid + NTHR * i; const int kk = e >> 4, n4 = (e & 15) * 4; const int n = nt * 64 + n4;
;         v[j][i] = (f32x4){0.f, 0.f, 0.f, 0.f};
;         if (t < nt4 && n < N) {
;           v[j][i] = *(const f32x4*)(src + (size_t)(kt * 64 + kk) * N + n);
;           if (gain) v[j][i] *= gain[kt * 64 + kk];
;         }
;       }
;     }
;     __syncthreads();
; #pragma unroll
;     for (int j = 0; j < 4; ++j)
; #pragma unroll
;       for (int i = 0; i < 2; ++i) {
;         const int e = tid + NTHR * i; const int kk = e >> 4, n4 = (e & 15) * 4;
;         float* tp = tile + j * TS + kk * 65 + n4;
;         tp[0] = v[j][i][0]; tp[1] = v[j][i][1]; tp[2] = v[j][i][2]; tp[3] = v[j][i][3];
;       }
;     __syncthreads();
; #pragma unroll
;     for (int j = 0; j < 4; ++j) {
;       const int t = t0 + j * gridDim.x;
;       if (t < nt4) {
;         const int kt = t % tk, nt = t / tk;
;         const int nn = tid >> 3, k8 = (tid & 7) * 8;
;         const float* tp = tile + j * TS + k8 * 65 + nn;
;         u32x4 u;
;         u.x = pack2(tp[0 * 65], tp[1 * 65]); u.y = pack2(tp[2 * 65], tp[3 * 65]);
;         u.z = pack2(tp[4 * 65], tp[5 * 65]); u.w = pack2(tp[6 * 65], tp[7 * 65]);
;         *(u32x4*)(dst + (size_t)(nt * 64 + nn) * K + kt * 64 + k8) = u;
.LBB0_217:
	s_or_b64 exec, exec, s[40:41]
	s_add_i32 s53, s52, s42
	s_ashr_i32 s38, s53, 31
	s_lshr_b32 s38, s38, 28
	s_add_i32 s38, s53, s38
	s_and_b32 s39, s38, 0x3fffff0
	s_sub_i32 s44, s53, s39
	s_lshl_b32 s39, s38, 2
	s_andn2_b32 s39, s39, 63
	v_or_b32_e32 v24, s39, v38
	s_cmpk_lt_i32 s53, 0x400
	s_cselect_b64 s[40:41], -1, 0
	v_cmp_gt_i32_e32 vcc, s50, v24
	v_ashrrev_i32_e32 v25, 31, v24
	s_and_b64 s[42:43], s[40:41], vcc
	s_lshl_b32 s38, s44, 6
	v_lshl_add_u64 v[34:35], v[24:25], 2, s[8:9]
	v_mov_b32_e32 v24, 0
	v_mov_b32_e32 v28, 0
	v_mov_b32_e32 v29, 0
	v_mov_b32_e32 v30, 0
	v_mov_b32_e32 v31, 0
	s_and_saveexec_b64 s[44:45], s[42:43]
	s_cbranch_execz .LBB0_220
	v_add_u32_e32 v26, s38, v41
	v_ashrrev_i32_e32 v27, 31, v26
	v_lshlrev_b64 v[28:29], 14, v[26:27]
	v_lshl_add_u64 v[28:29], v[34:35], 0, v[28:29]
	global_load_dwordx4 v[28:31], v[28:29], off
	s_and_b64 vcc, exec, s[4:5]
	s_cbranch_vccnz .LBB0_220
	v_lshl_add_u64 v[26:27], v[26:27], 2, s[22:23]
	global_load_dword v72, v[26:27], off
.LBB0_220:
	s_or_b64 exec, exec, s[44:45]
	v_mov_b32_e32 v25, 0
	v_mov_b32_e32 v26, 0
	v_mov_b32_e32 v27, 0
	s_and_saveexec_b64 s[44:45], s[42:43]
	s_cbranch_execz .LBB0_223
	v_add_u32_e32 v36, s38, v42
	v_ashrrev_i32_e32 v37, 31, v36
	v_lshlrev_b64 v[24:25], 14, v[36:37]
	v_lshl_add_u64 v[24:25], v[34:35], 0, v[24:25]
	global_load_dwordx4 v[24:27], v[24:25], off
	s_and_b64 vcc, exec, s[4:5]
	s_cbranch_vccnz .LBB0_223
	v_lshl_add_u64 v[34:35], v[36:37], 2, s[22:23]
	global_load_dword v74, v[34:35], off
.LBB0_223:
	s_or_b64 exec, exec, s[44:45]
	s_barrier
	s_waitcnt vmcnt(0)
	v_pk_mul_f32 v[6:7], v[6:7], v[60:61] op_sel_hi:[1,0]
	v_pk_mul_f32 v[4:5], v[4:5], v[60:61] op_sel_hi:[1,0]
	v_pk_mul_f32 v[2:3], v[2:3], v[62:63] op_sel_hi:[1,0]
	v_pk_mul_f32 v[0:1], v[0:1], v[62:63] op_sel_hi:[1,0]
	v_pk_mul_f32 v[14:15], v[14:15], v[64:65] op_sel_hi:[1,0]
	v_pk_mul_f32 v[12:13], v[12:13], v[64:65] op_sel_hi:[1,0]
	v_pk_mul_f32 v[10:11], v[10:11], v[66:67] op_sel_hi:[1,0]
	v_pk_mul_f32 v[8:9], v[8:9], v[66:67] op_sel_hi:[1,0]
	v_pk_mul_f32 v[22:23], v[22:23], v[68:69] op_sel_hi:[1,0]
	v_pk_mul_f32 v[20:21], v[20:21], v[68:69] op_sel_hi:[1,0]
	v_pk_mul_f32 v[18:19], v[18:19], v[70:71] op_sel_hi:[1,0]
	v_pk_mul_f32 v[16:17], v[16:17], v[70:71] op_sel_hi:[1,0]
	v_pk_mul_f32 v[30:31], v[30:31], v[72:73] op_sel_hi:[1,0]
	v_pk_mul_f32 v[28:29], v[28:29], v[72:73] op_sel_hi:[1,0]
	v_pk_mul_f32 v[26:27], v[26:27], v[74:75] op_sel_hi:[1,0]
	v_pk_mul_f32 v[24:25], v[24:25], v[74:75] op_sel_hi:[1,0]
	ds_write2_b32 v43, v4, v5 offset1:1
	ds_write2_b32 v43, v6, v7 offset0:2 offset1:3
	ds_write2_b32 v44, v0, v1 offset1:1
	ds_write2_b32 v44, v2, v3 offset0:2 offset1:3
	v_add_u32_e32 v0, 0x4100, v43
	ds_write2_b32 v0, v12, v13 offset1:1
	v_add_u32_e32 v0, 0x4108, v43
	ds_write2_b32 v0, v14, v15 offset1:1
	v_add_u32_e32 v0, 0x4100, v44
	ds_write2_b32 v0, v8, v9 offset1:1
	v_add_u32_e32 v0, 0x4108, v44
	ds_write2_b32 v0, v10, v11 offset1:1
	v_add_u32_e32 v0, 0x8200, v43
	ds_write2_b32 v0, v20, v21 offset1:1
	v_add_u32_e32 v0, 0x8208, v43
	ds_write2_b32 v0, v22, v23 offset1:1
	v_add_u32_e32 v0, 0x8200, v44
	ds_write2_b32 v0, v16, v17 offset1:1
	v_add_u32_e32 v0, 0x8208, v44
	ds_write2_b32 v0, v18, v19 offset1:1
	v_add_u32_e32 v0, 0xc300, v43
	ds_write2_b32 v0, v28, v29 offset1:1
	v_add_u32_e32 v0, 0xc308, v43
	ds_write2_b32 v0, v30, v31 offset1:1
	v_add_u32_e32 v0, 0xc300, v44
	ds_write2_b32 v0, v24, v25 offset1:1
	v_add_u32_e32 v0, 0xc308, v44
	ds_write2_b32 v0, v26, v27 offset1:1
	s_waitcnt lgkmcnt(0)
	s_barrier
	ds_read2_b32 v[0:1], v40 offset1:65
	ds_read2_b32 v[2:3], v40 offset0:130 offset1:195
	v_add_u32_e32 v6, 0x400, v40
	ds_read2_b32 v[4:5], v6 offset0:4 offset1:69
	ds_read2_b32 v[6:7], v6 offset0:134 offset1:199
	s_andn2_b64 vcc, exec, s[30:31]
	s_waitcnt lgkmcnt(3)
	v_cvt_pk_bf16_f32 v0, v0, v1
	s_waitcnt lgkmcnt(2)
	v_cvt_pk_bf16_f32 v1, v2, v3
	s_waitcnt lgkmcnt(1)
	v_cvt_pk_bf16_f32 v2, v4, v5
	v_add_u32_e32 v4, s29, v39
	v_ashrrev_i32_e32 v5, 31, v4
	v_lshlrev_b64 v[4:5], 11, v[4:5]
	v_lshl_add_u64 v[4:5], s[20:21], 0, v[4:5]
	s_ashr_i32 s29, s28, 31
	v_lshl_add_u64 v[4:5], s[28:29], 1, v[4:5]
	s_waitcnt lgkmcnt(0)
	v_cvt_pk_bf16_f32 v3, v6, v7
	v_lshl_add_u64 v[4:5], v[4:5], 0, v[32:33]
	global_store_dwordx4 v[4:5], v[0:3], off
	s_cbranch_vccz .LBB0_226
	s_andn2_b64 vcc, exec, s[36:37]
	s_cbranch_vccz .LBB0_227
